# v24 plus residual-epilogue quantisation: the 8 rowmax loads issued together after the panel wait, per-group vmcnt(0) drains removed
# speedup vs baseline: 1.0172x; 1.0036x over previous
;     __device__ __forceinline__ void operator()(const f32x4 (&acc)[2][2][4][2], const Unit& u, int wr, int wc, int fr_, int fq_) const {
;     ...
;         if (do_q) {
;             asm volatile("s_waitcnt vmcnt(0)" ::: "memory");
;             unsigned* pc = pcnt + 64 * u.pm;
;             if ((fr | fq) == 0) __hip_atomic_fetch_add(pc, 1u, __ATOMIC_RELAXED, __HIP_MEMORY_SCOPE_AGENT);
;             { unsigned sp = 0; while ((unsigned)__builtin_amdgcn_readfirstlane((int)__hip_atomic_load(pc, __ATOMIC_RELAXED, __HIP_MEMORY_SCOPE_AGENT)) < 64u && ++sp < (1u << 20)) __builtin_amdgcn_s_sleep(2); }
; #pragma unroll
;             for (int ai = 0; ai < 2; ++ai)
; #pragma unroll
;                 for (int m = 0; m < 4; ++m) {
;                     const int row = row0 + ai * HALF + m * 16;
;                     const float mx = __uint_as_float(__hip_atomic_load(rowmax + row, __ATOMIC_RELAXED, __HIP_MEMORY_SCOPE_AGENT)), inv = mx > 0.f ? 127.0f / mx : 0.f;
;                     if (u.pn == 0 && wc == 0 && fq == 0) sx[row] = mx * (1.0f / 127.0f);
; #pragma unroll
;                     for (int bj = 0; bj < 2; ++bj) {
;                         u32x2v o;
; #pragma unroll
;                         for (int h = 0; h < 2; ++h) {
;                             const unsigned w0 = xv[ai][m][bj][2 * h], w1 = xv[ai][m][bj][2 * h + 1];
;                             const int q0 = (int)__builtin_rintf(__uint_as_float(w0 << 16) * inv), q1 = (int)__builtin_rintf(__uint_as_float(w0 & 0xffff0000u) * inv);
;                             const int q2 = (int)__builtin_rintf(__uint_as_float(w1 << 16) * inv), q3 = (int)__builtin_rintf(__uint_as_float(w1 & 0xffff0000u) * inv);
;                             o[h] = (unsigned)(q0 & 255) | ((unsigned)(q1 & 255) << 8) | ((unsigned)(q2 & 255) << 16) | ((unsigned)q3 << 24);
;                         }
;                         *(u32x2v*)(XQ + (size_t)row * 2048 + col0 + bj * HALF) = o;
.LBB0_232:
	global_load_dword v102, v[2:3], off sc1
	global_load_dword v163, v[2:3], off offset:64 sc1
	global_load_dword v164, v[2:3], off offset:128 sc1
	global_load_dword v165, v[2:3], off offset:192 sc1
	global_load_dword v166, v[2:3], off offset:512 sc1
	global_load_dword v167, v[2:3], off offset:576 sc1
	global_load_dword v168, v[2:3], off offset:640 sc1
	global_load_dword v169, v[2:3], off offset:704 sc1
	s_or_b32 s4, s83, s43
	v_or_b32_e32 v4, s4, v205
	v_cmp_eq_u32_e64 s[6:7], 0, v4
	s_and_saveexec_b64 s[8:9], s[6:7]
	s_cbranch_execz .LBB0_234
	v_readlane_b32 s4, v252, 39
	v_readlane_b32 s5, v252, 40
	s_waitcnt vmcnt(0)
	v_mul_f32_e32 v103, 0x3c010204, v102
	v_lshl_add_u64 v[4:5], v[226:227], 2, s[4:5]
	global_store_dword v[4:5], v103, off
.LBB0_234:
	s_or_b64 exec, exec, s[8:9]
	s_waitcnt vmcnt(0)
	v_div_scale_f32 v103, s[4:5], v102, v102, s63
	v_rcp_f32_e32 v104, v103
	v_readlane_b32 s4, v252, 41
	v_readlane_b32 s5, v252, 42
	v_fma_f32 v105, -v103, v104, 1.0
	v_fmac_f32_e32 v104, v105, v104
	v_div_scale_f32 v105, vcc, s63, v102, s63
	v_mul_f32_e32 v114, v105, v104
	v_fma_f32 v115, -v103, v114, v105
	v_fmac_f32_e32 v114, v115, v104
	v_fma_f32 v103, -v103, v114, v105
	v_div_fmas_f32 v103, v103, v104, v114
	v_div_fixup_f32 v103, v103, v102, s63
	v_cmp_lt_f32_e32 vcc, 0, v102
	v_lshl_add_u64 v[4:5], s[4:5], 0, v[228:229]
	s_nop 0
	v_cndmask_b32_e32 v114, 0, v103, vcc
	v_mul_f32_e32 v105, v114, v158
	v_mul_f32_e32 v104, v114, v159
	v_rndne_f32_e32 v105, v105
	v_mul_f32_e32 v115, v114, v161
	v_mul_f32_e32 v116, v114, v160
	v_rndne_f32_e32 v104, v104
	v_cvt_i32_f32_e32 v105, v105
	v_rndne_f32_e32 v115, v115
	v_rndne_f32_e32 v116, v116
	v_cvt_i32_f32_e32 v104, v104
	v_cvt_i32_f32_sdwa v115, v115 dst_sel:WORD_1 dst_unused:UNUSED_PAD src0_sel:DWORD
	v_cvt_i32_f32_e32 v116, v116
	v_lshlrev_b32_e32 v105, 8, v105
	v_and_b32_e32 v105, 0xff00, v105
	v_and_b32_e32 v115, 0xff0000, v115
	v_perm_b32 v104, v116, v104, s94
	v_or3_b32 v104, v104, v105, v115
	v_mul_f32_e32 v115, v114, v150
	v_mul_f32_e32 v105, v114, v151
	v_rndne_f32_e32 v115, v115
	v_mul_f32_e32 v116, v114, v153
	v_mul_f32_e32 v117, v114, v152
	v_rndne_f32_e32 v105, v105
	v_cvt_i32_f32_e32 v115, v115
	v_rndne_f32_e32 v116, v116
	v_rndne_f32_e32 v117, v117
	v_cvt_i32_f32_e32 v105, v105
	v_cvt_i32_f32_sdwa v116, v116 dst_sel:WORD_1 dst_unused:UNUSED_PAD src0_sel:DWORD
	v_cvt_i32_f32_e32 v117, v117
	v_lshlrev_b32_e32 v115, 8, v115
	v_lshlrev_b64 v[102:103], 11, v[226:227]
	v_and_b32_e32 v115, 0xff00, v115
	v_and_b32_e32 v116, 0xff0000, v116
	v_perm_b32 v105, v117, v105, s94
	v_lshl_add_u64 v[102:103], v[4:5], 0, v[102:103]
	v_or3_b32 v105, v105, v115, v116
	global_store_dwordx2 v[102:103], v[104:105], off
	v_mul_f32_e32 v105, v114, v142
	v_mul_f32_e32 v104, v114, v143
	v_rndne_f32_e32 v105, v105
	v_mul_f32_e32 v115, v114, v186
	v_mul_f32_e32 v116, v114, v144
	v_rndne_f32_e32 v104, v104
	v_cvt_i32_f32_e32 v105, v105
	v_rndne_f32_e32 v115, v115
	v_rndne_f32_e32 v116, v116
	v_cvt_i32_f32_e32 v104, v104
	v_cvt_i32_f32_sdwa v115, v115 dst_sel:WORD_1 dst_unused:UNUSED_PAD src0_sel:DWORD
	v_cvt_i32_f32_e32 v116, v116
	v_lshlrev_b32_e32 v105, 8, v105
	v_and_b32_e32 v105, 0xff00, v105
	v_and_b32_e32 v115, 0xff0000, v115
	v_perm_b32 v104, v116, v104, s94
	v_or3_b32 v104, v104, v105, v115
	v_mul_f32_e32 v115, v114, v145
	v_mul_f32_e32 v105, v114, v187
	v_rndne_f32_e32 v115, v115
	v_mul_f32_e32 v116, v114, v137
	v_mul_f32_e32 v114, v114, v136
	v_rndne_f32_e32 v105, v105
	v_cvt_i32_f32_e32 v115, v115
	v_rndne_f32_e32 v116, v116
	v_rndne_f32_e32 v114, v114
	v_cvt_i32_f32_e32 v105, v105
	v_cvt_i32_f32_sdwa v116, v116 dst_sel:WORD_1 dst_unused:UNUSED_PAD src0_sel:DWORD
	v_cvt_i32_f32_e32 v114, v114
	v_lshlrev_b32_e32 v115, 8, v115
	v_and_b32_e32 v115, 0xff00, v115
	v_and_b32_e32 v116, 0xff0000, v116
	v_perm_b32 v105, v114, v105, s94
	v_or3_b32 v105, v105, v115, v116
	global_store_dwordx2 v[102:103], v[104:105], off offset:128
	s_nop 1
	v_mov_b32_e32 v102, v163
	s_and_saveexec_b64 s[8:9], s[6:7]
	s_cbranch_execz .LBB0_236
	v_readlane_b32 s4, v252, 39
	v_readlane_b32 s5, v252, 40
	v_mul_f32_e32 v103, 0x3c010204, v102
	v_lshl_add_u64 v[104:105], v[224:225], 2, s[4:5]
	global_store_dword v[104:105], v103, off
.LBB0_236:
	s_or_b64 exec, exec, s[8:9]
	v_div_scale_f32 v103, s[4:5], v102, v102, s63
	v_rcp_f32_e32 v104, v103
	v_div_scale_f32 v105, vcc, s63, v102, s63
	v_fma_f32 v114, -v103, v104, 1.0
	v_fmac_f32_e32 v104, v114, v104
	v_mul_f32_e32 v114, v105, v104
	v_fma_f32 v115, -v103, v114, v105
	v_fmac_f32_e32 v114, v115, v104
	v_fma_f32 v103, -v103, v114, v105
	v_div_fmas_f32 v103, v103, v104, v114
	v_div_fixup_f32 v103, v103, v102, s63
	v_cmp_lt_f32_e32 vcc, 0, v102
	s_nop 1
	v_cndmask_b32_e32 v114, 0, v103, vcc
	v_mul_f32_e32 v105, v114, v126
	v_mul_f32_e32 v104, v114, v127
	v_rndne_f32_e32 v105, v105
	v_mul_f32_e32 v115, v114, v129
	v_mul_f32_e32 v116, v114, v128
	v_rndne_f32_e32 v104, v104
	v_cvt_i32_f32_e32 v105, v105
	v_rndne_f32_e32 v115, v115
	v_rndne_f32_e32 v116, v116
	v_cvt_i32_f32_e32 v104, v104
	v_cvt_i32_f32_sdwa v115, v115 dst_sel:WORD_1 dst_unused:UNUSED_PAD src0_sel:DWORD
	v_cvt_i32_f32_e32 v116, v116
	v_lshlrev_b32_e32 v105, 8, v105
	v_and_b32_e32 v105, 0xff00, v105
	v_and_b32_e32 v115, 0xff0000, v115
	v_perm_b32 v104, v116, v104, s94
	v_or3_b32 v104, v104, v105, v115
	v_mul_f32_e32 v115, v114, v118
	v_mul_f32_e32 v105, v114, v119
	v_rndne_f32_e32 v115, v115
	v_mul_f32_e32 v116, v114, v121
	v_mul_f32_e32 v117, v114, v120
	v_rndne_f32_e32 v105, v105
	v_cvt_i32_f32_e32 v115, v115
	v_rndne_f32_e32 v116, v116
	v_rndne_f32_e32 v117, v117
	v_cvt_i32_f32_e32 v105, v105
;     __device__ __forceinline__ void operator()(const f32x4 (&acc)[2][2][4][2], const Unit& u, int wr, int wc, int fr_, int fq_) const {
;     ...
;             for (int ai = 0; ai < 2; ++ai)
; #pragma unroll
;                 for (int m = 0; m < 4; ++m) {
;                     const int row = row0 + ai * HALF + m * 16;
;                     const float mx = __uint_as_float(__hip_atomic_load(rowmax + row, __ATOMIC_RELAXED, __HIP_MEMORY_SCOPE_AGENT)), inv = mx > 0.f ? 127.0f / mx : 0.f;
;                     if (u.pn == 0 && wc == 0 && fq == 0) sx[row] = mx * (1.0f / 127.0f);
; #pragma unroll
;                     for (int bj = 0; bj < 2; ++bj) {
;                         u32x2v o;
; #pragma unroll
;                         for (int h = 0; h < 2; ++h) {
;                             const unsigned w0 = xv[ai][m][bj][2 * h], w1 = xv[ai][m][bj][2 * h + 1];
;                             const int q0 = (int)__builtin_rintf(__uint_as_float(w0 << 16) * inv), q1 = (int)__builtin_rintf(__uint_as_float(w0 & 0xffff0000u) * inv);
;                             const int q2 = (int)__builtin_rintf(__uint_as_float(w1 << 16) * inv), q3 = (int)__builtin_rintf(__uint_as_float(w1 & 0xffff0000u) * inv);
;                             o[h] = (unsigned)(q0 & 255) | ((unsigned)(q1 & 255) << 8) | ((unsigned)(q2 & 255) << 16) | ((unsigned)q3 << 24);
;                         }
;                         *(u32x2v*)(XQ + (size_t)row * 2048 + col0 + bj * HALF) = o;
;                     }
	v_cvt_i32_f32_sdwa v116, v116 dst_sel:WORD_1 dst_unused:UNUSED_PAD src0_sel:DWORD
	v_cvt_i32_f32_e32 v117, v117
	v_lshlrev_b32_e32 v115, 8, v115
	v_lshlrev_b64 v[102:103], 11, v[224:225]
	v_and_b32_e32 v115, 0xff00, v115
	v_and_b32_e32 v116, 0xff0000, v116
	v_perm_b32 v105, v117, v105, s94
	v_lshl_add_u64 v[102:103], v[4:5], 0, v[102:103]
	v_or3_b32 v105, v105, v115, v116
	global_store_dwordx2 v[102:103], v[104:105], off
	v_mul_f32_e32 v105, v114, v110
	v_mul_f32_e32 v104, v114, v111
	v_rndne_f32_e32 v105, v105
	v_mul_f32_e32 v110, v114, v113
	v_mul_f32_e32 v111, v114, v112
	v_rndne_f32_e32 v104, v104
	v_cvt_i32_f32_e32 v105, v105
	v_rndne_f32_e32 v110, v110
	v_rndne_f32_e32 v111, v111
	v_cvt_i32_f32_e32 v104, v104
	v_cvt_i32_f32_sdwa v110, v110 dst_sel:WORD_1 dst_unused:UNUSED_PAD src0_sel:DWORD
	v_cvt_i32_f32_e32 v111, v111
	v_lshlrev_b32_e32 v105, 8, v105
	v_and_b32_e32 v105, 0xff00, v105
	v_and_b32_e32 v110, 0xff0000, v110
	v_perm_b32 v104, v111, v104, s94
	v_mul_f32_e32 v106, v114, v106
	v_or3_b32 v104, v104, v105, v110
	v_mul_f32_e32 v105, v114, v107
	v_rndne_f32_e32 v106, v106
	v_mul_f32_e32 v107, v114, v109
	v_mul_f32_e32 v108, v114, v108
	v_rndne_f32_e32 v105, v105
	v_cvt_i32_f32_e32 v106, v106
	v_rndne_f32_e32 v107, v107
	v_rndne_f32_e32 v108, v108
	v_cvt_i32_f32_e32 v105, v105
	v_cvt_i32_f32_sdwa v107, v107 dst_sel:WORD_1 dst_unused:UNUSED_PAD src0_sel:DWORD
	v_cvt_i32_f32_e32 v108, v108
	v_lshlrev_b32_e32 v106, 8, v106
	v_and_b32_e32 v106, 0xff00, v106
	v_and_b32_e32 v107, 0xff0000, v107
	v_perm_b32 v105, v108, v105, s94
	v_or3_b32 v105, v105, v106, v107
	global_store_dwordx2 v[102:103], v[104:105], off offset:128
	s_nop 1
	v_mov_b32_e32 v102, v164
	s_and_saveexec_b64 s[8:9], s[6:7]
	s_cbranch_execz .LBB0_238
	v_readlane_b32 s4, v252, 39
	v_readlane_b32 s5, v252, 40
	v_mul_f32_e32 v103, 0x3c010204, v102
	v_lshl_add_u64 v[104:105], v[222:223], 2, s[4:5]
	global_store_dword v[104:105], v103, off
.LBB0_238:
	s_or_b64 exec, exec, s[8:9]
	v_div_scale_f32 v103, s[4:5], v102, v102, s63
	v_rcp_f32_e32 v104, v103
	v_div_scale_f32 v105, vcc, s63, v102, s63
	v_fma_f32 v106, -v103, v104, 1.0
	v_fmac_f32_e32 v104, v106, v104
	v_mul_f32_e32 v106, v105, v104
	v_fma_f32 v107, -v103, v106, v105
	v_fmac_f32_e32 v106, v107, v104
	v_fma_f32 v103, -v103, v106, v105
	v_div_fmas_f32 v103, v103, v104, v106
	v_div_fixup_f32 v103, v103, v102, s63
	v_cmp_lt_f32_e32 vcc, 0, v102
	s_nop 1
	v_cndmask_b32_e32 v104, 0, v103, vcc
	v_mul_f32_e32 v94, v104, v94
	v_mul_f32_e32 v90, v104, v90
	v_mul_f32_e32 v86, v104, v86
	v_mul_f32_e32 v82, v104, v82
	v_mul_f32_e32 v95, v104, v95
	v_rndne_f32_e32 v94, v94
	v_mul_f32_e32 v97, v104, v97
	v_mul_f32_e32 v96, v104, v96
	v_mul_f32_e32 v91, v104, v91
	v_rndne_f32_e32 v90, v90
	v_mul_f32_e32 v93, v104, v93
	v_mul_f32_e32 v92, v104, v92
	v_mul_f32_e32 v87, v104, v87
	v_rndne_f32_e32 v86, v86
	v_mul_f32_e32 v89, v104, v89
	v_mul_f32_e32 v88, v104, v88
	v_mul_f32_e32 v83, v104, v83
	v_rndne_f32_e32 v82, v82
	v_mul_f32_e32 v85, v104, v85
	v_mul_f32_e32 v84, v104, v84
	v_rndne_f32_e32 v95, v95
	v_cvt_i32_f32_e32 v94, v94
	v_rndne_f32_e32 v97, v97
	v_rndne_f32_e32 v96, v96
	v_rndne_f32_e32 v91, v91
	v_cvt_i32_f32_e32 v90, v90
	v_rndne_f32_e32 v93, v93
	v_rndne_f32_e32 v92, v92
	v_rndne_f32_e32 v87, v87
	v_cvt_i32_f32_e32 v86, v86
	v_rndne_f32_e32 v89, v89
	v_rndne_f32_e32 v88, v88
	v_rndne_f32_e32 v83, v83
	v_cvt_i32_f32_e32 v82, v82
	v_rndne_f32_e32 v85, v85
	v_rndne_f32_e32 v84, v84
	v_cvt_i32_f32_e32 v95, v95
	v_cvt_i32_f32_sdwa v97, v97 dst_sel:WORD_1 dst_unused:UNUSED_PAD src0_sel:DWORD
	v_cvt_i32_f32_e32 v96, v96
	v_cvt_i32_f32_e32 v91, v91
	v_cvt_i32_f32_sdwa v93, v93 dst_sel:WORD_1 dst_unused:UNUSED_PAD src0_sel:DWORD
	v_cvt_i32_f32_e32 v92, v92
	v_cvt_i32_f32_e32 v87, v87
	v_cvt_i32_f32_sdwa v89, v89 dst_sel:WORD_1 dst_unused:UNUSED_PAD src0_sel:DWORD
	v_cvt_i32_f32_e32 v88, v88
	v_cvt_i32_f32_e32 v83, v83
	v_cvt_i32_f32_sdwa v85, v85 dst_sel:WORD_1 dst_unused:UNUSED_PAD src0_sel:DWORD
	v_cvt_i32_f32_e32 v84, v84
	v_lshlrev_b32_e32 v94, 8, v94
	v_lshlrev_b32_e32 v90, 8, v90
	v_lshlrev_b32_e32 v86, 8, v86
	v_lshlrev_b32_e32 v82, 8, v82
	v_lshlrev_b64 v[102:103], 11, v[222:223]
	v_and_b32_e32 v94, 0xff00, v94
	v_and_b32_e32 v97, 0xff0000, v97
	v_perm_b32 v95, v96, v95, s94
	v_and_b32_e32 v90, 0xff00, v90
	v_and_b32_e32 v93, 0xff0000, v93
	v_perm_b32 v91, v92, v91, s94
	v_and_b32_e32 v86, 0xff00, v86
	v_and_b32_e32 v89, 0xff0000, v89
	v_perm_b32 v87, v88, v87, s94
	v_and_b32_e32 v82, 0xff00, v82
	v_and_b32_e32 v85, 0xff0000, v85
	v_perm_b32 v83, v84, v83, s94
	v_lshl_add_u64 v[102:103], v[4:5], 0, v[102:103]
	v_or3_b32 v94, v95, v94, v97
	v_or3_b32 v95, v91, v90, v93
	v_or3_b32 v86, v87, v86, v89
	v_or3_b32 v87, v83, v82, v85
	global_store_dwordx2 v[102:103], v[94:95], off
	global_store_dwordx2 v[102:103], v[86:87], off offset:128
	s_nop 1
	v_mov_b32_e32 v82, v165
	s_and_saveexec_b64 s[8:9], s[6:7]
	s_cbranch_execz .LBB0_240
	v_readlane_b32 s4, v252, 39
	v_readlane_b32 s5, v252, 40
	v_mul_f32_e32 v83, 0x3c010204, v82
	v_lshl_add_u64 v[84:85], v[220:221], 2, s[4:5]
	global_store_dword v[84:85], v83, off
;     __device__ __forceinline__ void operator()(const f32x4 (&acc)[2][2][4][2], const Unit& u, int wr, int wc, int fr_, int fq_) const {
;     ...
;             for (int ai = 0; ai < 2; ++ai)
; #pragma unroll
;                 for (int m = 0; m < 4; ++m) {
;                     const int row = row0 + ai * HALF + m * 16;
;                     const float mx = __uint_as_float(__hip_atomic_load(rowmax + row, __ATOMIC_RELAXED, __HIP_MEMORY_SCOPE_AGENT)), inv = mx > 0.f ? 127.0f / mx : 0.f;
;                     if (u.pn == 0 && wc == 0 && fq == 0) sx[row] = mx * (1.0f / 127.0f);
; #pragma unroll
;                     for (int bj = 0; bj < 2; ++bj) {
;                         u32x2v o;
; #pragma unroll
;                         for (int h = 0; h < 2; ++h) {
;                             const unsigned w0 = xv[ai][m][bj][2 * h], w1 = xv[ai][m][bj][2 * h + 1];
;                             const int q0 = (int)__builtin_rintf(__uint_as_float(w0 << 16) * inv), q1 = (int)__builtin_rintf(__uint_as_float(w0 & 0xffff0000u) * inv);
;                             const int q2 = (int)__builtin_rintf(__uint_as_float(w1 << 16) * inv), q3 = (int)__builtin_rintf(__uint_as_float(w1 & 0xffff0000u) * inv);
;                             o[h] = (unsigned)(q0 & 255) | ((unsigned)(q1 & 255) << 8) | ((unsigned)(q2 & 255) << 16) | ((unsigned)q3 << 24);
;                         }
;                         *(u32x2v*)(XQ + (size_t)row * 2048 + col0 + bj * HALF) = o;
;                     }
.LBB0_240:
	s_or_b64 exec, exec, s[8:9]
	v_div_scale_f32 v83, s[4:5], v82, v82, s63
	v_rcp_f32_e32 v84, v83
	v_div_scale_f32 v85, vcc, s63, v82, s63
	v_fma_f32 v86, -v83, v84, 1.0
	v_fmac_f32_e32 v84, v86, v84
	v_mul_f32_e32 v86, v85, v84
	v_fma_f32 v87, -v83, v86, v85
	v_fmac_f32_e32 v86, v87, v84
	v_fma_f32 v83, -v83, v86, v85
	v_div_fmas_f32 v83, v83, v84, v86
	v_div_fixup_f32 v83, v83, v82, s63
	v_cmp_lt_f32_e32 vcc, 0, v82
	s_nop 1
	v_cndmask_b32_e32 v84, 0, v83, vcc
	v_mul_f32_e32 v78, v84, v78
	v_mul_f32_e32 v74, v84, v74
	v_mul_f32_e32 v70, v84, v70
	v_mul_f32_e32 v66, v84, v66
	v_mul_f32_e32 v79, v84, v79
	v_rndne_f32_e32 v78, v78
	v_mul_f32_e32 v81, v84, v81
	v_mul_f32_e32 v80, v84, v80
	v_mul_f32_e32 v75, v84, v75
	v_rndne_f32_e32 v74, v74
	v_mul_f32_e32 v77, v84, v77
	v_mul_f32_e32 v76, v84, v76
	v_mul_f32_e32 v71, v84, v71
	v_rndne_f32_e32 v70, v70
	v_mul_f32_e32 v73, v84, v73
	v_mul_f32_e32 v72, v84, v72
	v_mul_f32_e32 v67, v84, v67
	v_rndne_f32_e32 v66, v66
	v_mul_f32_e32 v69, v84, v69
	v_mul_f32_e32 v68, v84, v68
	v_rndne_f32_e32 v79, v79
	v_cvt_i32_f32_e32 v78, v78
	v_rndne_f32_e32 v81, v81
	v_rndne_f32_e32 v80, v80
	v_rndne_f32_e32 v75, v75
	v_cvt_i32_f32_e32 v74, v74
	v_rndne_f32_e32 v77, v77
	v_rndne_f32_e32 v76, v76
	v_rndne_f32_e32 v71, v71
	v_cvt_i32_f32_e32 v70, v70
	v_rndne_f32_e32 v73, v73
	v_rndne_f32_e32 v72, v72
	v_rndne_f32_e32 v67, v67
	v_cvt_i32_f32_e32 v66, v66
	v_rndne_f32_e32 v69, v69
	v_rndne_f32_e32 v68, v68
	v_cvt_i32_f32_e32 v79, v79
	v_cvt_i32_f32_sdwa v81, v81 dst_sel:WORD_1 dst_unused:UNUSED_PAD src0_sel:DWORD
	v_cvt_i32_f32_e32 v80, v80
	v_cvt_i32_f32_e32 v75, v75
	v_cvt_i32_f32_sdwa v77, v77 dst_sel:WORD_1 dst_unused:UNUSED_PAD src0_sel:DWORD
	v_cvt_i32_f32_e32 v76, v76
	v_cvt_i32_f32_e32 v71, v71
	v_cvt_i32_f32_sdwa v73, v73 dst_sel:WORD_1 dst_unused:UNUSED_PAD src0_sel:DWORD
	v_cvt_i32_f32_e32 v72, v72
	v_cvt_i32_f32_e32 v67, v67
	v_cvt_i32_f32_sdwa v69, v69 dst_sel:WORD_1 dst_unused:UNUSED_PAD src0_sel:DWORD
	v_cvt_i32_f32_e32 v68, v68
	v_lshlrev_b32_e32 v78, 8, v78
	v_lshlrev_b32_e32 v74, 8, v74
	v_lshlrev_b32_e32 v70, 8, v70
	v_lshlrev_b32_e32 v66, 8, v66
	v_lshlrev_b64 v[82:83], 11, v[220:221]
	v_and_b32_e32 v78, 0xff00, v78
	v_and_b32_e32 v81, 0xff0000, v81
	v_perm_b32 v79, v80, v79, s94
	v_and_b32_e32 v74, 0xff00, v74
	v_and_b32_e32 v77, 0xff0000, v77
	v_perm_b32 v75, v76, v75, s94
	v_and_b32_e32 v70, 0xff00, v70
	v_and_b32_e32 v73, 0xff0000, v73
	v_perm_b32 v71, v72, v71, s94
	v_and_b32_e32 v66, 0xff00, v66
	v_and_b32_e32 v69, 0xff0000, v69
	v_perm_b32 v67, v68, v67, s94
	v_lshl_add_u64 v[82:83], v[4:5], 0, v[82:83]
	v_or3_b32 v78, v79, v78, v81
	v_or3_b32 v79, v75, v74, v77
	v_or3_b32 v70, v71, v70, v73
	v_or3_b32 v71, v67, v66, v69
	global_store_dwordx2 v[82:83], v[78:79], off
	global_store_dwordx2 v[82:83], v[70:71], off offset:128
	s_nop 1
	v_mov_b32_e32 v66, v166
	s_and_saveexec_b64 s[8:9], s[6:7]
	s_cbranch_execz .LBB0_242
	v_readlane_b32 s4, v252, 39
	v_readlane_b32 s5, v252, 40
	v_mul_f32_e32 v67, 0x3c010204, v66
	v_lshl_add_u64 v[68:69], v[218:219], 2, s[4:5]
	global_store_dword v[68:69], v67, off
.LBB0_242:
	s_or_b64 exec, exec, s[8:9]
	v_div_scale_f32 v67, s[4:5], v66, v66, s63
	v_rcp_f32_e32 v68, v67
	v_div_scale_f32 v69, vcc, s63, v66, s63
	v_fma_f32 v70, -v67, v68, 1.0
	v_fmac_f32_e32 v68, v70, v68
	v_mul_f32_e32 v70, v69, v68
	v_fma_f32 v71, -v67, v70, v69
	v_fmac_f32_e32 v70, v71, v68
	v_fma_f32 v67, -v67, v70, v69
	v_div_fmas_f32 v67, v67, v68, v70
	v_div_fixup_f32 v67, v67, v66, s63
	v_cmp_lt_f32_e32 vcc, 0, v66
	s_nop 1
	v_cndmask_b32_e32 v68, 0, v67, vcc
	v_mul_f32_e32 v62, v68, v62
	v_mul_f32_e32 v58, v68, v58
	v_mul_f32_e32 v54, v68, v54
	v_mul_f32_e32 v50, v68, v50
	v_mul_f32_e32 v63, v68, v63
	v_rndne_f32_e32 v62, v62
	v_mul_f32_e32 v65, v68, v65
	v_mul_f32_e32 v64, v68, v64
	v_mul_f32_e32 v59, v68, v59
	v_rndne_f32_e32 v58, v58
	v_mul_f32_e32 v61, v68, v61
	v_mul_f32_e32 v60, v68, v60
	v_mul_f32_e32 v55, v68, v55
	v_rndne_f32_e32 v54, v54
	v_mul_f32_e32 v57, v68, v57
	v_mul_f32_e32 v56, v68, v56
	v_mul_f32_e32 v51, v68, v51
	v_rndne_f32_e32 v50, v50
	v_mul_f32_e32 v53, v68, v53
	v_mul_f32_e32 v52, v68, v52
	v_rndne_f32_e32 v63, v63
	v_cvt_i32_f32_e32 v62, v62
	v_rndne_f32_e32 v65, v65
	v_rndne_f32_e32 v64, v64
	v_rndne_f32_e32 v59, v59
	v_cvt_i32_f32_e32 v58, v58
	v_rndne_f32_e32 v61, v61
	v_rndne_f32_e32 v60, v60
	v_rndne_f32_e32 v55, v55
	v_cvt_i32_f32_e32 v54, v54
	v_rndne_f32_e32 v57, v57
	v_rndne_f32_e32 v56, v56
	v_rndne_f32_e32 v51, v51
	v_cvt_i32_f32_e32 v50, v50
	v_rndne_f32_e32 v53, v53
	v_rndne_f32_e32 v52, v52
	v_cvt_i32_f32_e32 v63, v63
	v_cvt_i32_f32_sdwa v65, v65 dst_sel:WORD_1 dst_unused:UNUSED_PAD src0_sel:DWORD
	v_cvt_i32_f32_e32 v64, v64
	v_cvt_i32_f32_e32 v59, v59
	v_cvt_i32_f32_sdwa v61, v61 dst_sel:WORD_1 dst_unused:UNUSED_PAD src0_sel:DWORD
	v_cvt_i32_f32_e32 v60, v60
	v_cvt_i32_f32_e32 v55, v55
	v_cvt_i32_f32_sdwa v57, v57 dst_sel:WORD_1 dst_unused:UNUSED_PAD src0_sel:DWORD
	v_cvt_i32_f32_e32 v56, v56
	v_cvt_i32_f32_e32 v51, v51
	v_cvt_i32_f32_sdwa v53, v53 dst_sel:WORD_1 dst_unused:UNUSED_PAD src0_sel:DWORD
	v_cvt_i32_f32_e32 v52, v52
	v_lshlrev_b32_e32 v62, 8, v62
	v_lshlrev_b32_e32 v58, 8, v58
	v_lshlrev_b32_e32 v54, 8, v54
	v_lshlrev_b32_e32 v50, 8, v50
	v_lshlrev_b64 v[66:67], 11, v[218:219]
	v_and_b32_e32 v62, 0xff00, v62
	v_and_b32_e32 v65, 0xff0000, v65
	v_perm_b32 v63, v64, v63, s94
	v_and_b32_e32 v58, 0xff00, v58
	v_and_b32_e32 v61, 0xff0000, v61
	v_perm_b32 v59, v60, v59, s94
	v_and_b32_e32 v54, 0xff00, v54
	v_and_b32_e32 v57, 0xff0000, v57
	v_perm_b32 v55, v56, v55, s94
	v_and_b32_e32 v50, 0xff00, v50
	v_and_b32_e32 v53, 0xff0000, v53
	v_perm_b32 v51, v52, v51, s94
	v_lshl_add_u64 v[66:67], v[4:5], 0, v[66:67]
	v_or3_b32 v62, v63, v62, v65
	v_or3_b32 v63, v59, v58, v61
	v_or3_b32 v54, v55, v54, v57
	v_or3_b32 v55, v51, v50, v53
	global_store_dwordx2 v[66:67], v[62:63], off
	global_store_dwordx2 v[66:67], v[54:55], off offset:128
	s_nop 1
	v_mov_b32_e32 v50, v167
	s_and_saveexec_b64 s[8:9], s[6:7]
	s_cbranch_execz .LBB0_244
	v_readlane_b32 s4, v252, 39
	v_readlane_b32 s5, v252, 40
	v_mul_f32_e32 v51, 0x3c010204, v50
	v_lshl_add_u64 v[52:53], v[216:217], 2, s[4:5]
	global_store_dword v[52:53], v51, off
;     __device__ __forceinline__ void operator()(const f32x4 (&acc)[2][2][4][2], const Unit& u, int wr, int wc, int fr_, int fq_) const {
;     ...
;             for (int ai = 0; ai < 2; ++ai)
; #pragma unroll
;                 for (int m = 0; m < 4; ++m) {
;                     const int row = row0 + ai * HALF + m * 16;
;                     const float mx = __uint_as_float(__hip_atomic_load(rowmax + row, __ATOMIC_RELAXED, __HIP_MEMORY_SCOPE_AGENT)), inv = mx > 0.f ? 127.0f / mx : 0.f;
;                     if (u.pn == 0 && wc == 0 && fq == 0) sx[row] = mx * (1.0f / 127.0f);
; #pragma unroll
;                     for (int bj = 0; bj < 2; ++bj) {
;                         u32x2v o;
; #pragma unroll
;                         for (int h = 0; h < 2; ++h) {
;                             const unsigned w0 = xv[ai][m][bj][2 * h], w1 = xv[ai][m][bj][2 * h + 1];
;                             const int q0 = (int)__builtin_rintf(__uint_as_float(w0 << 16) * inv), q1 = (int)__builtin_rintf(__uint_as_float(w0 & 0xffff0000u) * inv);
;                             const int q2 = (int)__builtin_rintf(__uint_as_float(w1 << 16) * inv), q3 = (int)__builtin_rintf(__uint_as_float(w1 & 0xffff0000u) * inv);
;                             o[h] = (unsigned)(q0 & 255) | ((unsigned)(q1 & 255) << 8) | ((unsigned)(q2 & 255) << 16) | ((unsigned)q3 << 24);
;                         }
;                         *(u32x2v*)(XQ + (size_t)row * 2048 + col0 + bj * HALF) = o;
;                     }
.LBB0_244:
	s_or_b64 exec, exec, s[8:9]
	v_div_scale_f32 v51, s[4:5], v50, v50, s63
	v_rcp_f32_e32 v52, v51
	v_div_scale_f32 v53, vcc, s63, v50, s63
	v_fma_f32 v54, -v51, v52, 1.0
	v_fmac_f32_e32 v52, v54, v52
	v_mul_f32_e32 v54, v53, v52
	v_fma_f32 v55, -v51, v54, v53
	v_fmac_f32_e32 v54, v55, v52
	v_fma_f32 v51, -v51, v54, v53
	v_div_fmas_f32 v51, v51, v52, v54
	v_div_fixup_f32 v51, v51, v50, s63
	v_cmp_lt_f32_e32 vcc, 0, v50
	s_nop 1
	v_cndmask_b32_e32 v52, 0, v51, vcc
	v_mul_f32_e32 v46, v52, v46
	v_mul_f32_e32 v42, v52, v42
	v_mul_f32_e32 v38, v52, v38
	v_mul_f32_e32 v34, v52, v34
	v_mul_f32_e32 v47, v52, v47
	v_rndne_f32_e32 v46, v46
	v_mul_f32_e32 v49, v52, v49
	v_mul_f32_e32 v48, v52, v48
	v_mul_f32_e32 v43, v52, v43
	v_rndne_f32_e32 v42, v42
	v_mul_f32_e32 v45, v52, v45
	v_mul_f32_e32 v44, v52, v44
	v_mul_f32_e32 v39, v52, v39
	v_rndne_f32_e32 v38, v38
	v_mul_f32_e32 v41, v52, v41
	v_mul_f32_e32 v40, v52, v40
	v_mul_f32_e32 v35, v52, v35
	v_rndne_f32_e32 v34, v34
	v_mul_f32_e32 v37, v52, v37
	v_mul_f32_e32 v36, v52, v36
	v_rndne_f32_e32 v47, v47
	v_cvt_i32_f32_e32 v46, v46
	v_rndne_f32_e32 v49, v49
	v_rndne_f32_e32 v48, v48
	v_rndne_f32_e32 v43, v43
	v_cvt_i32_f32_e32 v42, v42
	v_rndne_f32_e32 v45, v45
	v_rndne_f32_e32 v44, v44
	v_rndne_f32_e32 v39, v39
	v_cvt_i32_f32_e32 v38, v38
	v_rndne_f32_e32 v41, v41
	v_rndne_f32_e32 v40, v40
	v_rndne_f32_e32 v35, v35
	v_cvt_i32_f32_e32 v34, v34
	v_rndne_f32_e32 v37, v37
	v_rndne_f32_e32 v36, v36
	v_cvt_i32_f32_e32 v47, v47
	v_cvt_i32_f32_sdwa v49, v49 dst_sel:WORD_1 dst_unused:UNUSED_PAD src0_sel:DWORD
	v_cvt_i32_f32_e32 v48, v48
	v_cvt_i32_f32_e32 v43, v43
	v_cvt_i32_f32_sdwa v45, v45 dst_sel:WORD_1 dst_unused:UNUSED_PAD src0_sel:DWORD
	v_cvt_i32_f32_e32 v44, v44
	v_cvt_i32_f32_e32 v39, v39
	v_cvt_i32_f32_sdwa v41, v41 dst_sel:WORD_1 dst_unused:UNUSED_PAD src0_sel:DWORD
	v_cvt_i32_f32_e32 v40, v40
	v_cvt_i32_f32_e32 v35, v35
	v_cvt_i32_f32_sdwa v37, v37 dst_sel:WORD_1 dst_unused:UNUSED_PAD src0_sel:DWORD
	v_cvt_i32_f32_e32 v36, v36
	v_lshlrev_b32_e32 v46, 8, v46
	v_lshlrev_b32_e32 v42, 8, v42
	v_lshlrev_b32_e32 v38, 8, v38
	v_lshlrev_b32_e32 v34, 8, v34
	v_lshlrev_b64 v[50:51], 11, v[216:217]
	v_and_b32_e32 v46, 0xff00, v46
	v_and_b32_e32 v49, 0xff0000, v49
	v_perm_b32 v47, v48, v47, s94
	v_and_b32_e32 v42, 0xff00, v42
	v_and_b32_e32 v45, 0xff0000, v45
	v_perm_b32 v43, v44, v43, s94
	v_and_b32_e32 v38, 0xff00, v38
	v_and_b32_e32 v41, 0xff0000, v41
	v_perm_b32 v39, v40, v39, s94
	v_and_b32_e32 v34, 0xff00, v34
	v_and_b32_e32 v37, 0xff0000, v37
	v_perm_b32 v35, v36, v35, s94
	v_lshl_add_u64 v[50:51], v[4:5], 0, v[50:51]
	v_or3_b32 v46, v47, v46, v49
	v_or3_b32 v47, v43, v42, v45
	v_or3_b32 v38, v39, v38, v41
	v_or3_b32 v39, v35, v34, v37
	global_store_dwordx2 v[50:51], v[46:47], off
	global_store_dwordx2 v[50:51], v[38:39], off offset:128
	s_nop 1
	v_mov_b32_e32 v34, v168
	s_and_saveexec_b64 s[8:9], s[6:7]
	s_cbranch_execz .LBB0_246
	v_readlane_b32 s4, v252, 39
	v_readlane_b32 s5, v252, 40
	v_mul_f32_e32 v35, 0x3c010204, v34
	v_lshl_add_u64 v[36:37], v[214:215], 2, s[4:5]
	global_store_dword v[36:37], v35, off
;     __device__ __forceinline__ void operator()(const f32x4 (&acc)[2][2][4][2], const Unit& u, int wr, int wc, int fr_, int fq_) const {
;     ...
;             for (int ai = 0; ai < 2; ++ai)
; #pragma unroll
;                 for (int m = 0; m < 4; ++m) {
;                     const int row = row0 + ai * HALF + m * 16;
;                     const float mx = __uint_as_float(__hip_atomic_load(rowmax + row, __ATOMIC_RELAXED, __HIP_MEMORY_SCOPE_AGENT)), inv = mx > 0.f ? 127.0f / mx : 0.f;
;                     if (u.pn == 0 && wc == 0 && fq == 0) sx[row] = mx * (1.0f / 127.0f);
; #pragma unroll
;                     for (int bj = 0; bj < 2; ++bj) {
;                         u32x2v o;
; #pragma unroll
;                         for (int h = 0; h < 2; ++h) {
;                             const unsigned w0 = xv[ai][m][bj][2 * h], w1 = xv[ai][m][bj][2 * h + 1];
;                             const int q0 = (int)__builtin_rintf(__uint_as_float(w0 << 16) * inv), q1 = (int)__builtin_rintf(__uint_as_float(w0 & 0xffff0000u) * inv);
;                             const int q2 = (int)__builtin_rintf(__uint_as_float(w1 << 16) * inv), q3 = (int)__builtin_rintf(__uint_as_float(w1 & 0xffff0000u) * inv);
;                             o[h] = (unsigned)(q0 & 255) | ((unsigned)(q1 & 255) << 8) | ((unsigned)(q2 & 255) << 16) | ((unsigned)q3 << 24);
;                         }
;                         *(u32x2v*)(XQ + (size_t)row * 2048 + col0 + bj * HALF) = o;
;                     }
.LBB0_246:
	s_or_b64 exec, exec, s[8:9]
	v_div_scale_f32 v35, s[4:5], v34, v34, s63
	v_rcp_f32_e32 v36, v35
	v_div_scale_f32 v37, vcc, s63, v34, s63
	v_fma_f32 v38, -v35, v36, 1.0
	v_fmac_f32_e32 v36, v38, v36
	v_mul_f32_e32 v38, v37, v36
	v_fma_f32 v39, -v35, v38, v37
	v_fmac_f32_e32 v38, v39, v36
	v_fma_f32 v35, -v35, v38, v37
	v_div_fmas_f32 v35, v35, v36, v38
	v_div_fixup_f32 v35, v35, v34, s63
	v_cmp_lt_f32_e32 vcc, 0, v34
	s_nop 1
	v_cndmask_b32_e32 v36, 0, v35, vcc
	v_mul_f32_e32 v30, v36, v30
	v_mul_f32_e32 v26, v36, v26
	v_mul_f32_e32 v22, v36, v22
	v_mul_f32_e32 v18, v36, v18
	v_mul_f32_e32 v31, v36, v31
	v_rndne_f32_e32 v30, v30
	v_mul_f32_e32 v33, v36, v33
	v_mul_f32_e32 v32, v36, v32
	v_mul_f32_e32 v27, v36, v27
	v_rndne_f32_e32 v26, v26
	v_mul_f32_e32 v29, v36, v29
	v_mul_f32_e32 v28, v36, v28
	v_mul_f32_e32 v23, v36, v23
	v_rndne_f32_e32 v22, v22
	v_mul_f32_e32 v25, v36, v25
	v_mul_f32_e32 v24, v36, v24
	v_mul_f32_e32 v19, v36, v19
	v_rndne_f32_e32 v18, v18
	v_mul_f32_e32 v21, v36, v21
	v_mul_f32_e32 v20, v36, v20
	v_rndne_f32_e32 v31, v31
	v_cvt_i32_f32_e32 v30, v30
	v_rndne_f32_e32 v33, v33
	v_rndne_f32_e32 v32, v32
	v_rndne_f32_e32 v27, v27
	v_cvt_i32_f32_e32 v26, v26
	v_rndne_f32_e32 v29, v29
	v_rndne_f32_e32 v28, v28
	v_rndne_f32_e32 v23, v23
	v_cvt_i32_f32_e32 v22, v22
	v_rndne_f32_e32 v25, v25
	v_rndne_f32_e32 v24, v24
	v_rndne_f32_e32 v19, v19
	v_cvt_i32_f32_e32 v18, v18
	v_rndne_f32_e32 v21, v21
	v_rndne_f32_e32 v20, v20
	v_cvt_i32_f32_e32 v31, v31
	v_cvt_i32_f32_sdwa v33, v33 dst_sel:WORD_1 dst_unused:UNUSED_PAD src0_sel:DWORD
	v_cvt_i32_f32_e32 v32, v32
	v_cvt_i32_f32_e32 v27, v27
	v_cvt_i32_f32_sdwa v29, v29 dst_sel:WORD_1 dst_unused:UNUSED_PAD src0_sel:DWORD
	v_cvt_i32_f32_e32 v28, v28
	v_cvt_i32_f32_e32 v23, v23
	v_cvt_i32_f32_sdwa v25, v25 dst_sel:WORD_1 dst_unused:UNUSED_PAD src0_sel:DWORD
	v_cvt_i32_f32_e32 v24, v24
	v_cvt_i32_f32_e32 v19, v19
	v_cvt_i32_f32_sdwa v21, v21 dst_sel:WORD_1 dst_unused:UNUSED_PAD src0_sel:DWORD
	v_cvt_i32_f32_e32 v20, v20
	v_lshlrev_b32_e32 v30, 8, v30
	v_lshlrev_b32_e32 v26, 8, v26
	v_lshlrev_b32_e32 v22, 8, v22
	v_lshlrev_b32_e32 v18, 8, v18
	v_lshlrev_b64 v[34:35], 11, v[214:215]
	v_and_b32_e32 v30, 0xff00, v30
	v_and_b32_e32 v33, 0xff0000, v33
	v_perm_b32 v31, v32, v31, s94
	v_and_b32_e32 v26, 0xff00, v26
	v_and_b32_e32 v29, 0xff0000, v29
	v_perm_b32 v27, v28, v27, s94
	v_and_b32_e32 v22, 0xff00, v22
	v_and_b32_e32 v25, 0xff0000, v25
	v_perm_b32 v23, v24, v23, s94
	v_and_b32_e32 v18, 0xff00, v18
	v_and_b32_e32 v21, 0xff0000, v21
	v_perm_b32 v19, v20, v19, s94
	v_lshl_add_u64 v[34:35], v[4:5], 0, v[34:35]
	v_or3_b32 v30, v31, v30, v33
	v_or3_b32 v31, v27, v26, v29
	v_or3_b32 v22, v23, v22, v25
	v_or3_b32 v23, v19, v18, v21
	global_store_dwordx2 v[34:35], v[30:31], off
	global_store_dwordx2 v[34:35], v[22:23], off offset:128
	s_nop 1
	v_mov_b32_e32 v2, v169
	s_and_saveexec_b64 s[8:9], s[6:7]
	s_cbranch_execz .LBB0_248
	v_readlane_b32 s4, v252, 39
	v_readlane_b32 s5, v252, 40
	v_mul_f32_e32 v3, 0x3c010204, v2
	v_lshl_add_u64 v[18:19], v[212:213], 2, s[4:5]
	global_store_dword v[18:19], v3, off
.LBB0_248:
	s_or_b64 exec, exec, s[8:9]
	v_div_scale_f32 v3, s[4:5], v2, v2, s63
	v_rcp_f32_e32 v18, v3
	v_div_scale_f32 v19, vcc, s63, v2, s63
	v_fma_f32 v20, -v3, v18, 1.0
	v_fmac_f32_e32 v18, v20, v18
	v_mul_f32_e32 v20, v19, v18
	v_fma_f32 v21, -v3, v20, v19
	v_fmac_f32_e32 v20, v21, v18
	v_fma_f32 v3, -v3, v20, v19
	v_div_fmas_f32 v3, v3, v18, v20
	v_div_fixup_f32 v3, v3, v2, s63
	v_cmp_lt_f32_e32 vcc, 0, v2
	s_nop 1
	v_cndmask_b32_e32 v18, 0, v3, vcc
	v_lshlrev_b64 v[2:3], 11, v[212:213]
	v_lshl_add_u64 v[2:3], v[4:5], 0, v[2:3]
	v_mul_f32_e32 v5, v18, v14
	v_mul_f32_e32 v4, v18, v15
	v_rndne_f32_e32 v5, v5
	v_mul_f32_e32 v14, v18, v17
	v_mul_f32_e32 v15, v18, v16
	v_rndne_f32_e32 v4, v4
	v_cvt_i32_f32_e32 v5, v5
	v_rndne_f32_e32 v14, v14
	v_rndne_f32_e32 v15, v15
	v_cvt_i32_f32_e32 v4, v4
	v_cvt_i32_f32_sdwa v14, v14 dst_sel:WORD_1 dst_unused:UNUSED_PAD src0_sel:DWORD
	v_cvt_i32_f32_e32 v15, v15
	v_lshlrev_b32_e32 v5, 8, v5
	v_and_b32_e32 v5, 0xff00, v5
	v_and_b32_e32 v14, 0xff0000, v14
	v_perm_b32 v4, v15, v4, s94
	v_mul_f32_e32 v10, v18, v10
	v_or3_b32 v4, v4, v5, v14
	v_mul_f32_e32 v5, v18, v11
	v_rndne_f32_e32 v10, v10
	v_mul_f32_e32 v11, v18, v13
	v_mul_f32_e32 v12, v18, v12
	v_rndne_f32_e32 v5, v5
	v_cvt_i32_f32_e32 v10, v10
	v_rndne_f32_e32 v11, v11
	v_rndne_f32_e32 v12, v12
	v_cvt_i32_f32_e32 v5, v5
	v_cvt_i32_f32_sdwa v11, v11 dst_sel:WORD_1 dst_unused:UNUSED_PAD src0_sel:DWORD
	v_cvt_i32_f32_e32 v12, v12
	v_lshlrev_b32_e32 v10, 8, v10
	v_and_b32_e32 v10, 0xff00, v10
	v_and_b32_e32 v11, 0xff0000, v11
	v_perm_b32 v5, v12, v5, s94
	v_or3_b32 v5, v5, v10, v11
	global_store_dwordx2 v[2:3], v[4:5], off
	v_mul_f32_e32 v5, v18, v6
	v_mul_f32_e32 v4, v18, v7
	v_rndne_f32_e32 v5, v5
	v_mul_f32_e32 v6, v18, v98
	v_mul_f32_e32 v7, v18, v8
	v_rndne_f32_e32 v4, v4
	v_cvt_i32_f32_e32 v5, v5
	v_rndne_f32_e32 v6, v6
	v_rndne_f32_e32 v7, v7
	v_cvt_i32_f32_e32 v4, v4
	v_cvt_i32_f32_sdwa v6, v6 dst_sel:WORD_1 dst_unused:UNUSED_PAD src0_sel:DWORD
	v_cvt_i32_f32_e32 v7, v7
	v_lshlrev_b32_e32 v5, 8, v5
	v_and_b32_e32 v5, 0xff00, v5
	v_and_b32_e32 v6, 0xff0000, v6
	v_perm_b32 v4, v7, v4, s94
	v_or3_b32 v4, v4, v5, v6
	v_mul_f32_e32 v6, v18, v9
	v_mul_f32_e32 v5, v18, v99
	v_rndne_f32_e32 v6, v6
	v_mul_f32_e32 v7, v18, v101
	v_mul_f32_e32 v8, v18, v100
	v_rndne_f32_e32 v5, v5
	v_cvt_i32_f32_e32 v6, v6
	v_rndne_f32_e32 v7, v7
	v_rndne_f32_e32 v8, v8
	v_cvt_i32_f32_e32 v5, v5
	v_cvt_i32_f32_sdwa v7, v7 dst_sel:WORD_1 dst_unused:UNUSED_PAD src0_sel:DWORD
	v_cvt_i32_f32_e32 v8, v8
	v_lshlrev_b32_e32 v6, 8, v6
	v_and_b32_e32 v6, 0xff00, v6
	v_and_b32_e32 v7, 0xff0000, v7
	v_perm_b32 v5, v8, v5, s94
	v_or3_b32 v5, v5, v6, v7
	global_store_dwordx2 v[2:3], v[4:5], off offset:128
